# attention softmax: 1/8 scale and log2e folded into one fma constant (running maxima kept in scaled units), 64 fewer VALU per key tile per wave; hazard pads re-derived
# baseline (speedup 1.0000x reference)
; #define LAS __attribute__((address_space(3)))
; __device__ __forceinline__ PP get_params() { unsigned long long kp = (unsigned long long)__builtin_amdgcn_kernarg_segment_ptr(); asm volatile("" : "+s"(kp)); return (PP)kp; }
; __device__ __forceinline__ int opaque_bid() { int t = blockIdx.x; asm volatile("" : "+s"(t)); return t; }
; __device__ __forceinline__ float shx(float v, int mask, int lane) { return __int_as_float(__builtin_amdgcn_ds_bpermute((lane ^ mask) << 2, __float_as_int(v))); }
; __device__ __forceinline__ void attn_phase(int wv, PP P, int L, LAS unsigned char* lds) {
;     ...
;                         for (int q = 0; q < 4; ++q) { const bool kv = (kt > 0) || (nt * 16 + fq * 4 + q >= 48); sa[nt][q] = kv ? sa[nt][q] * 0.125f : -INFINITY; mx = fmaxf(mx, sa[nt][q]); }
;                     mx = fmaxf(mx, shx(mx, 16, lane)); mx = fmaxf(mx, shx(mx, 32, lane));
;                     const float mnew = fmaxf(mrun[m], mx); const float alpha = __expf(mrun[m] - mnew); mrun[m] = mnew;
; __device__ __forceinline__ void fill_convert(int wv, LAS unsigned char* lds, int nunits, int L, int mask) {
;     const int G = (int)gridDim.x, extra = nunits % G, bid = opaque_bid();
;     if (extra != 0 && bid >= extra) convert_layer(wv, get_params(), L, mask, (LAS float*)lds, bid - extra, G - extra);
; }
.LBB0_159:
	s_or_b64 exec, exec, s[4:5]
	s_abs_i32 s4, s48
	s_waitcnt lgkmcnt(0)
	v_cvt_f32_u32_e32 v0, s4
	s_mul_i32 s93, s49, s48
	s_mul_i32 s93, s93, s2
	s_sub_i32 s2, 0, s4
	v_rcp_iflag_f32_e32 v0, v0
	s_ashr_i32 s49, s48, 31
	s_lshl_b32 s92, s48, 9
	s_mov_b32 s57, 0
	v_mul_f32_e32 v0, 0x4f7ffffe, v0
	v_cvt_u32_f32_e32 v0, v0
	v_mov_b32_e32 v3, 0
	s_mov_b32 s86, 0xfffe0
	s_movk_i32 s66, 0x2000
	v_readfirstlane_b32 s5, v0
	s_mul_i32 s2, s2, s5
	s_mul_hi_u32 s2, s5, s2
	s_add_i32 s5, s5, s2
	s_mul_hi_u32 s2, s5, 0xdaa
	s_mul_i32 s2, s2, s4
	s_sub_i32 s2, 0xdaa, s2
	s_sub_i32 s6, s2, s4
	s_cmp_ge_u32 s2, s4
	s_cselect_b32 s2, s6, s2
	s_sub_i32 s6, s2, s4
	s_cmp_ge_u32 s2, s4
	s_cselect_b32 s2, s6, s2
	s_cmp_eq_u32 s2, 0
	s_cselect_b64 s[6:7], -1, 0
	v_writelane_b32 v254, s6, 1
	s_sub_i32 s3, s48, s2
	v_mov_b32_e32 v220, 0x358637bd
	v_writelane_b32 v254, s7, 2
	v_writelane_b32 v254, s2, 3
	s_mul_hi_u32 s2, s5, 0x210
	s_mul_i32 s2, s2, s4
	s_sub_i32 s2, 0x210, s2
	s_sub_i32 s6, s2, s4
	s_cmp_ge_u32 s2, s4
	s_cselect_b32 s2, s6, s2
	s_sub_i32 s6, s2, s4
	s_cmp_ge_u32 s2, s4
	s_cselect_b32 s2, s6, s2
	s_cmp_eq_u32 s2, 0
	s_cselect_b64 s[82:83], -1, 0
	v_writelane_b32 v254, s2, 4
	s_sub_i32 s33, s48, s2
	s_mul_hi_u32 s2, s5, 0xb58
	s_mul_i32 s2, s2, s4
	s_sub_i32 s2, 0xb58, s2
	s_sub_i32 s5, s2, s4
	s_cmp_ge_u32 s2, s4
	s_cselect_b32 s2, s5, s2
	s_sub_i32 s5, s2, s4
	s_cmp_ge_u32 s2, s4
	s_cselect_b32 s2, s5, s2
	s_cmp_eq_u32 s2, 0
	s_cselect_b64 s[4:5], -1, 0
	v_writelane_b32 v254, s4, 5
	s_lshl_b32 s84, s48, 10
	s_lshl_b32 s85, s48, 14
	v_writelane_b32 v254, s5, 6
	v_writelane_b32 v254, s2, 7
	s_sub_i32 s2, s48, s2
	v_writelane_b32 v254, s2, 8
	s_lshl_b32 s2, s48, 12
	v_writelane_b32 v254, s2, 9
	s_lshl_b32 s2, s48, 5
	v_writelane_b32 v254, s2, 10
	s_add_i32 s2, 0, 0x16b00
	v_writelane_b32 v254, s2, 11
	s_add_i32 s2, 0, 0x1bf00
	v_writelane_b32 v254, s2, 12
	s_add_i32 s2, 0, 0x1c100
	v_writelane_b32 v254, s2, 13
	s_add_i32 s2, 0, 0x1c200
	v_writelane_b32 v254, s2, 14
	s_add_i32 s2, 0, 0x1c500
	v_writelane_b32 v254, s2, 15
	s_add_i32 s2, 0, 0x17f00
	v_writelane_b32 v254, s2, 16
	s_add_i32 s2, 0, 0x10800
	v_writelane_b32 v254, s2, 17
	s_add_i32 s2, 0, 0x1c300
	v_writelane_b32 v254, s2, 18
	s_add_i32 s2, 0, 0x19b00
	v_writelane_b32 v254, s2, 19
	v_writelane_b32 v254, s81, 20
	v_writelane_b32 v254, s82, 21
	s_add_i32 s88, 0, 0x253f0
	s_add_i32 s89, 0, 0x253f4
	v_writelane_b32 v254, s83, 22
	v_writelane_b32 v254, s84, 23
	v_writelane_b32 v254, s85, 24
	v_writelane_b32 v254, s88, 25
	s_mov_b32 s96, 0x800000
	s_movk_i32 s94, 0x1000
	s_movk_i32 s87, 0x104
	v_mov_b32_e32 v221, 0x1000
	v_mov_b32_e32 v222, 0x2000
	v_mov_b32_e32 v223, 0x285dd000
	v_mov_b32_e32 v224, 1
	s_movk_i32 s97, 0x3800
	s_mov_b32 s52, 0xff800000
	s_add_i32 s53, 0, 0x1c0fc
	s_add_i32 s60, 0, 0x1c1fc
	s_movk_i32 s61, 0x3000
	s_mov_b32 s50, 0x3e38aa3b
	s_mov_b32 s67, 0x210000
	s_movk_i32 s51, 0x5800
	v_mov_b32_e32 v225, 0xbf3a00e3
	v_mov_b32_e32 v196, 0x3f317218
	v_mov_b32_e32 v226, 0x7f800000
	v_mov_b32_e32 v227, 0xff800000
	v_mov_b32_e32 v228, 0x840
	v_mov_b32_e32 v229, 0x1ce0000
	v_mov_b64_e32 v[198:199], 0x20f
	v_mov_b64_e32 v[200:201], 0x210
	s_mov_b32 s54, 0x3e6d3388
	s_mov_b64 s[10:11], -1
	s_mov_b64 s[58:59], 0x80
	s_mov_b64 s[62:63], 0xe0000
	s_mov_b64 s[64:65], 0x2000
	s_mov_b32 s34, s57
	v_writelane_b32 v254, s89, 26
	s_barrier
	v_writelane_b32 v254, s3, 27
	s_branch .LBB0_162

; #define LAS __attribute__((address_space(3)))
; __device__ __forceinline__ float shx(float v, int mask, int lane) { return __int_as_float(__builtin_amdgcn_ds_bpermute((lane ^ mask) << 2, __float_as_int(v))); }
; __device__ __forceinline__ unsigned pack2(float lo, float hi) { unsigned r; asm("v_cvt_pk_bf16_f32 %0, %1, %2" : "=v"(r) : "v"(lo), "v"(hi)); return r; }
; __device__ __forceinline__ void attn_phase(int wv, PP P, int L, LAS unsigned char* lds) {
;     ...
;                         for (int kk = 0; kk < 2; ++kk) { const bf16x8 kf = *(const LAS bf16x8*)(lds + kbuf + (nt * 16 + fr) * 272 + (m * 64 + kk * 32 + fq * 8) * 2);
;                             sa[nt] = __builtin_amdgcn_mfma_f32_16x16x32_bf16(kf, qf[m][kk], sa[nt], 0, 0, 0); } }
;                     float mx = -INFINITY;
; #pragma unroll
;                     for (int nt = 0; nt < 4; ++nt)
; #pragma unroll
;                         for (int q = 0; q < 4; ++q) { const bool kv = (kt > 0) || (nt * 16 + fq * 4 + q >= 48); sa[nt][q] = kv ? sa[nt][q] * 0.125f : -INFINITY; mx = fmaxf(mx, sa[nt][q]); }
;                     mx = fmaxf(mx, shx(mx, 16, lane)); mx = fmaxf(mx, shx(mx, 32, lane));
;                     const float mnew = fmaxf(mrun[m], mx); const float alpha = __expf(mrun[m] - mnew); mrun[m] = mnew;
;                     float rsum = 0.f;
; #pragma unroll
;                     for (int nt = 0; nt < 4; ++nt)
; #pragma unroll
;                         for (int q = 0; q < 4; ++q) { sa[nt][q] = __expf(sa[nt][q] - mnew); rsum += sa[nt][q]; }
;                     rsum += shx(rsum, 16, lane); rsum += shx(rsum, 32, lane);
;                     lrun[m] = lrun[m] * alpha + rsum;
; #pragma unroll
;                     for (int e = 0; e < 8; ++e) O[m][e] *= alpha;
; #pragma unroll
;                     for (int kp = 0; kp < 2; ++kp) { u32x4 t; t.x = pack2(sa[2 * kp][0], sa[2 * kp][1]); t.y = pack2(sa[2 * kp][2], sa[2 * kp][3]); t.z = pack2(sa[2 * kp + 1][0], sa[2 * kp + 1][1]); t.w = pack2(sa[2 * kp + 1][2], sa[2 * kp + 1][3]);
;                         pf[m][kp] = __builtin_bit_cast(bf16x8, t); }
.LBB0_365:
	s_and_b64 s[26:27], s[6:7], s[18:19]
	v_cndmask_b32_e64 v36, 0, 1, s[26:27]
	s_lshl_b32 s24, s24, 1
	v_readfirstlane_b32 s9, v36
	s_sub_i32 s9, s24, s9
	s_and_b64 s[26:27], s[4:5], exec
	s_cselect_b32 s25, s9, -1
	s_cmp_lt_i32 s25, 0
	s_cbranch_scc1 .LBB0_367
	ds_read_b128 v[36:39], v171 offset:13056
	ds_read_b128 v[40:43], v171 offset:13120
	s_waitcnt vmcnt(1) lgkmcnt(1)
	v_mfma_f32_16x16x32_bf16 v[36:39], v[36:39], v[12:15], 0
	ds_read_b128 v[44:47], v171 offset:13248
	s_waitcnt lgkmcnt(1)
	v_mfma_f32_16x16x32_bf16 v[36:39], v[40:43], v[4:7], v[36:39]
	s_nop 7
	v_max3_f32 v40, v36, s52, v37
	v_max3_f32 v40, v40, v38, v39
	v_mov_b32_e32 v41, v40
	s_nop 1
	v_permlane16_swap_b32_e32 v40, v41
	s_waitcnt lgkmcnt(0)
	v_max_f32_e32 v41, v41, v41
	v_max_f32_e32 v40, v40, v41
	v_mov_b32_e32 v41, v40
	s_nop 1
	v_permlane32_swap_b32_e32 v40, v41
	s_waitcnt lgkmcnt(0)
	v_max_f32_e32 v40, v40, v41
	v_mul_f32_e32 v96, s50, v40
	v_fma_f32 v36, v36, s50, -v96
	v_exp_f32_e32 v53, v36
	v_fma_f32 v36, v37, s50, -v96
	v_exp_f32_e32 v57, v36
	v_fma_f32 v36, v38, s50, -v96
	v_sub_f32_e32 v40, 0xff800000, v96
	v_exp_f32_e32 v55, v36
	v_fma_f32 v36, v39, s50, -v96
	v_exp_f32_e32 v49, v40
	v_exp_f32_e32 v59, v36
	v_cvt_pk_bf16_f32 v36, v49, v49
	v_cvt_pk_bf16_f32 v40, v53, v57
	s_nop 0
	v_mov_b32_e32 v38, v36
	v_mov_b32_e32 v39, v36
	v_mov_b32_e32 v37, v36
	v_mov_b64_e32 v[66:67], v[38:39]
	v_mov_b32_e32 v66, v40
	ds_read_b128 v[40:43], v171 offset:13184
	s_waitcnt lgkmcnt(0)
	v_mfma_f32_16x16x32_bf16 v[40:43], v[40:43], v[8:11], 0
	v_cvt_pk_bf16_f32 v67, v55, v59
	v_mov_b64_e32 v[64:65], v[36:37]
	s_waitcnt vmcnt(0)
	v_mfma_f32_16x16x32_bf16 v[40:43], v[44:47], v[16:19], v[40:43]
	s_nop 7
	v_max3_f32 v44, v40, s52, v41
	v_max3_f32 v44, v44, v42, v43
	v_mov_b32_e32 v45, v44
	s_nop 1
	v_permlane16_swap_b32_e32 v44, v45
	s_waitcnt lgkmcnt(0)
	v_max_f32_e32 v45, v45, v45
	v_max_f32_e32 v44, v44, v45
	v_mov_b32_e32 v45, v44
	s_nop 1
	v_permlane32_swap_b32_e32 v44, v45
	s_waitcnt lgkmcnt(0)
	v_max_f32_e32 v44, v44, v45
	v_mul_f32_e32 v117, s50, v44
	v_sub_f32_e32 v44, 0xff800000, v117
	v_exp_f32_e32 v48, v44
	v_fma_f32 v40, v40, s50, -v117
	v_exp_f32_e32 v52, v40
	v_pk_add_f32 v[44:45], v[48:49], 0 op_sel_hi:[1,0]
	v_fma_f32 v40, v41, s50, -v117
	v_pk_add_f32 v[44:45], v[48:49], v[44:45]
	v_pk_add_f32 v[44:45], v[48:49], v[44:45]
	v_exp_f32_e32 v56, v40
	v_pk_add_f32 v[44:45], v[48:49], v[44:45]
	v_fma_f32 v40, v42, s50, -v117
	v_pk_add_f32 v[44:45], v[48:49], v[44:45]
	v_pk_add_f32 v[44:45], v[48:49], v[44:45]
	v_exp_f32_e32 v54, v40
	v_pk_add_f32 v[44:45], v[48:49], v[44:45]
	v_fma_f32 v40, v43, s50, -v117
	v_pk_add_f32 v[44:45], v[48:49], v[44:45]
	v_pk_add_f32 v[44:45], v[48:49], v[44:45]
	v_exp_f32_e32 v58, v40
	v_pk_add_f32 v[40:41], v[48:49], v[44:45]
	s_nop 0
	v_pk_add_f32 v[40:41], v[48:49], v[40:41]
	s_nop 0
	v_pk_add_f32 v[40:41], v[48:49], v[40:41]
	s_nop 0
	v_pk_add_f32 v[40:41], v[52:53], v[40:41]
	v_cvt_pk_bf16_f32 v52, v52, v56
	s_nop 0
	v_pk_add_f32 v[40:41], v[56:57], v[40:41]
	s_nop 0
	v_pk_add_f32 v[40:41], v[54:55], v[40:41]
	s_nop 0
	v_pk_add_f32 v[40:41], v[58:59], v[40:41]
	v_mov_b32_e32 v43, v41
	v_mov_b32_e32 v42, v40
	s_nop 0
	v_permlane16_swap_b32_e32 v41, v43
	v_permlane16_swap_b32_e32 v40, v42
	s_waitcnt lgkmcnt(0)
	v_pk_add_f32 v[40:41], v[40:41], v[42:43]
	v_mov_b32_e32 v43, v41
	v_mov_b32_e32 v42, v40
	s_nop 0
	v_permlane32_swap_b32_e32 v41, v43
	v_permlane32_swap_b32_e32 v40, v42
	s_waitcnt lgkmcnt(0)
; __device__ __forceinline__ float shx(float v, int mask, int lane) { return __int_as_float(__builtin_amdgcn_ds_bpermute((lane ^ mask) << 2, __float_as_int(v))); }
; __device__ __forceinline__ u32x2 trr(unsigned addr) { u32x2 r; asm volatile("ds_read_b64_tr_b16 %0, %1" : "=&v"(r) : "v"(addr) : "memory"); return r; }
; __device__ __forceinline__ void trw4(u32x2& a, u32x2& b, u32x2& c, u32x2& d) { asm volatile("s_waitcnt lgkmcnt(0)" : "+v"(a), "+v"(b), "+v"(c), "+v"(d) : : "memory"); }
; __device__ __forceinline__ unsigned pack2(float lo, float hi) { unsigned r; asm("v_cvt_pk_bf16_f32 %0, %1, %2" : "=v"(r) : "v"(lo), "v"(hi)); return r; }
; __device__ __forceinline__ void attn_phase(int wv, PP P, int L, LAS unsigned char* lds) {
;     ...
;                     rsum += shx(rsum, 16, lane); rsum += shx(rsum, 32, lane);
;                     lrun[m] = lrun[m] * alpha + rsum;
; #pragma unroll
;                     for (int e = 0; e < 8; ++e) O[m][e] *= alpha;
; #pragma unroll
;                     for (int kp = 0; kp < 2; ++kp) { u32x4 t; t.x = pack2(sa[2 * kp][0], sa[2 * kp][1]); t.y = pack2(sa[2 * kp][2], sa[2 * kp][3]); t.z = pack2(sa[2 * kp + 1][0], sa[2 * kp + 1][1]); t.w = pack2(sa[2 * kp + 1][2], sa[2 * kp + 1][3]);
;                         pf[m][kp] = __builtin_bit_cast(bf16x8, t); }
;                 }
;                 const unsigned trv = ldsb + vbuf + (4 * fq + trq) * 272 + (4 * trp) * 2;
; #pragma unroll
;                 for (int kp = 0; kp < 2; ++kp) {
;                     u32x2 vl[8], vh[8];
; #pragma unroll
;                     for (int e = 0; e < 8; ++e) { vl[e] = trr(trv + (32 * kp) * 272 + e * 32); vh[e] = trr(trv + (32 * kp + 16) * 272 + e * 32); }
;                     trw4(vl[0], vl[1], vl[2], vl[3]); trw4(vl[4], vl[5], vl[6], vl[7]); trw4(vh[0], vh[1], vh[2], vh[3]); trw4(vh[4], vh[5], vh[6], vh[7]);
; #pragma unroll
;                     for (int e = 0; e < 8; ++e) { const bf16x8 vf = mk8(vl[e], vh[e]);
;                         O[0][e] = __builtin_amdgcn_mfma_f32_16x16x32_bf16(vf, pf[0][kp], O[0][e], 0, 0, 0);
;                         O[1][e] = __builtin_amdgcn_mfma_f32_16x16x32_bf16(vf, pf[1][kp], O[1][e], 0, 0, 0); }
;                 }
	v_pk_add_f32 v[42:43], v[40:41], v[42:43]
	v_pk_mul_f32 v[40:41], v[48:49], 0 op_sel_hi:[1,0]
	v_pk_fma_f32 v[134:135], v[48:49], 0, v[42:43] op_sel_hi:[1,0,1]
	v_cvt_pk_bf16_f32 v48, v48, v48
	v_mov_b32_e32 v44, v41
	v_mov_b32_e32 v50, v48
	v_mov_b32_e32 v51, v48
	v_mov_b32_e32 v49, v48
	v_mov_b64_e32 v[94:95], v[50:51]
	v_mov_b32_e32 v94, v52
	ds_read_b64_tr_b16 v[52:53], v172
	v_cvt_pk_bf16_f32 v95, v54, v58
	ds_read_b64_tr_b16 v[54:55], v173
	ds_read_b64_tr_b16 v[56:57], v174
	ds_read_b64_tr_b16 v[58:59], v175
	ds_read_b64_tr_b16 v[60:61], v176
	ds_read_b64_tr_b16 v[62:63], v177
	ds_read_b64_tr_b16 v[68:69], v178
	ds_read_b64_tr_b16 v[70:71], v179
	ds_read_b64_tr_b16 v[72:73], v180
	ds_read_b64_tr_b16 v[74:75], v181
	ds_read_b64_tr_b16 v[76:77], v182
	ds_read_b64_tr_b16 v[78:79], v183
	ds_read_b64_tr_b16 v[80:81], v184
	ds_read_b64_tr_b16 v[82:83], v185
	ds_read_b64_tr_b16 v[84:85], v186
	ds_read_b64_tr_b16 v[86:87], v187
	s_nop 0
	s_waitcnt lgkmcnt(0)
	v_mov_b32_e32 v45, v41
	s_waitcnt lgkmcnt(0)
	s_waitcnt lgkmcnt(0)
	v_mov_b32_e32 v46, v41
	v_mov_b32_e32 v47, v41
	s_waitcnt lgkmcnt(0)
	v_mov_b32_e32 v41, v40
	v_mov_b32_e32 v42, v40
	v_mfma_f32_16x16x32_bf16 v[88:91], v[52:55], v[36:39], v[44:47]
	v_mov_b32_e32 v43, v40
	v_mov_b64_e32 v[92:93], v[48:49]
	v_mfma_f32_16x16x32_bf16 v[98:101], v[56:59], v[36:39], v[44:47]
	v_mfma_f32_16x16x32_bf16 v[102:105], v[60:63], v[36:39], v[44:47]
	v_mfma_f32_16x16x32_bf16 v[106:109], v[68:71], v[36:39], v[44:47]
	v_mfma_f32_16x16x32_bf16 v[110:113], v[72:75], v[36:39], v[44:47]
	v_mfma_f32_16x16x32_bf16 v[136:139], v[76:79], v[36:39], v[44:47]
	v_mfma_f32_16x16x32_bf16 v[144:147], v[80:83], v[36:39], v[44:47]
	v_mfma_f32_16x16x32_bf16 v[152:155], v[84:87], v[36:39], v[44:47]
	ds_read_b64_tr_b16 v[36:37], v188
	ds_read_b64_tr_b16 v[38:39], v189
	v_mfma_f32_16x16x32_bf16 v[52:55], v[52:55], v[48:51], v[40:43]
	v_mfma_f32_16x16x32_bf16 v[56:59], v[56:59], v[48:51], v[40:43]
	v_mfma_f32_16x16x32_bf16 v[60:63], v[60:63], v[48:51], v[40:43]
	v_mfma_f32_16x16x32_bf16 v[68:71], v[68:71], v[48:51], v[40:43]
	v_mfma_f32_16x16x32_bf16 v[118:121], v[72:75], v[48:51], v[40:43]
	v_mfma_f32_16x16x32_bf16 v[140:143], v[76:79], v[48:51], v[40:43]
	v_mfma_f32_16x16x32_bf16 v[148:151], v[80:83], v[48:51], v[40:43]
	v_mfma_f32_16x16x32_bf16 v[156:159], v[84:87], v[48:51], v[40:43]
	ds_read_b64_tr_b16 v[40:41], v190
	ds_read_b64_tr_b16 v[42:43], v191
	ds_read_b64_tr_b16 v[44:45], v192
	ds_read_b64_tr_b16 v[46:47], v193
	ds_read_b64_tr_b16 v[160:161], v194
	ds_read_b64_tr_b16 v[162:163], v195
	ds_read_b64_tr_b16 v[210:211], v197
	ds_read_b64_tr_b16 v[212:213], v202
	ds_read_b64_tr_b16 v[214:215], v203
	ds_read_b64_tr_b16 v[216:217], v204
	ds_read_b64_tr_b16 v[230:231], v205
	ds_read_b64_tr_b16 v[232:233], v206
	ds_read_b64_tr_b16 v[234:235], v207
	ds_read_b64_tr_b16 v[236:237], v208
	s_nop 0
	s_waitcnt lgkmcnt(0)
	s_waitcnt lgkmcnt(0)
	s_waitcnt lgkmcnt(0)
	s_waitcnt lgkmcnt(0)
	s_nop 0
	v_mfma_f32_16x16x32_bf16 v[72:75], v[36:39], v[64:67], v[88:91]
	v_mfma_f32_16x16x32_bf16 v[48:51], v[36:39], v[92:95], v[52:55]
	v_mfma_f32_16x16x32_bf16 v[84:87], v[40:43], v[64:67], v[98:101]
	v_mfma_f32_16x16x32_bf16 v[40:43], v[40:43], v[92:95], v[56:59]
	v_mfma_f32_16x16x32_bf16 v[80:83], v[44:47], v[64:67], v[102:105]
	v_mfma_f32_16x16x32_bf16 v[36:39], v[44:47], v[92:95], v[60:63]
	v_mfma_f32_16x16x32_bf16 v[76:79], v[160:163], v[64:67], v[106:109]
	v_mfma_f32_16x16x32_bf16 v[44:47], v[160:163], v[92:95], v[68:71]
	v_mfma_f32_16x16x32_bf16 v[88:91], v[210:213], v[64:67], v[110:113]
	v_mfma_f32_16x16x32_bf16 v[52:55], v[210:213], v[92:95], v[118:121]
	v_mfma_f32_16x16x32_bf16 v[108:111], v[214:217], v[64:67], v[136:139]
	v_mfma_f32_16x16x32_bf16 v[56:59], v[214:217], v[92:95], v[140:143]
	v_mfma_f32_16x16x32_bf16 v[112:115], v[230:233], v[64:67], v[144:147]
	v_mfma_f32_16x16x32_bf16 v[60:63], v[230:233], v[92:95], v[148:151]
	v_mfma_f32_16x16x32_bf16 v[68:71], v[234:237], v[64:67], v[152:155]
	v_mfma_f32_16x16x32_bf16 v[64:67], v[234:237], v[92:95], v[156:159]
	s_andn2_b64 vcc, exec, s[6:7]
	s_cbranch_vccz .LBB0_368
	s_branch .LBB0_375

; #define LAS __attribute__((address_space(3)))
; __device__ __forceinline__ float shx(float v, int mask, int lane) { return __int_as_float(__builtin_amdgcn_ds_bpermute((lane ^ mask) << 2, __float_as_int(v))); }
; __device__ __forceinline__ void attn_phase(int wv, PP P, int L, LAS unsigned char* lds) {
;     ...
; #pragma unroll
;                 for (int m = 0; m < 2; ++m) {
;                     f32x4 sa[4];
; #pragma unroll
;                     for (int nt = 0; nt < 4; ++nt) { sa[nt] = (f32x4){0.f, 0.f, 0.f, 0.f};
; #pragma unroll
;                         for (int kk = 0; kk < 2; ++kk) { const bf16x8 kf = *(const LAS bf16x8*)(lds + kbuf + (nt * 16 + fr) * 272 + (m * 64 + kk * 32 + fq * 8) * 2);
;                             sa[nt] = __builtin_amdgcn_mfma_f32_16x16x32_bf16(kf, qf[m][kk], sa[nt], 0, 0, 0); } }
;                     float mx = -INFINITY;
; #pragma unroll
;                     for (int nt = 0; nt < 4; ++nt)
; #pragma unroll
;                         for (int q = 0; q < 4; ++q) { const bool kv = (kt > 0) || (nt * 16 + fq * 4 + q >= 48); sa[nt][q] = kv ? sa[nt][q] * 0.125f : -INFINITY; mx = fmaxf(mx, sa[nt][q]); }
;                     mx = fmaxf(mx, shx(mx, 16, lane)); mx = fmaxf(mx, shx(mx, 32, lane));
;                     const float mnew = fmaxf(mrun[m], mx); const float alpha = __expf(mrun[m] - mnew); mrun[m] = mnew;
;                     float rsum = 0.f;
; #pragma unroll
;                     for (int nt = 0; nt < 4; ++nt)
; #pragma unroll
;                         for (int q = 0; q < 4; ++q) { sa[nt][q] = __expf(sa[nt][q] - mnew); rsum += sa[nt][q]; }
;                     rsum += shx(rsum, 16, lane); rsum += shx(rsum, 32, lane);
;                     lrun[m] = lrun[m] * alpha + rsum;
; #pragma unroll
;                     for (int e = 0; e < 8; ++e) O[m][e] *= alpha;
.LBB0_373:
	v_add_u32_e32 v122, s7, v171
	ds_read_b128 v[92:95], v122
	ds_read_b128 v[98:101], v122 offset:64
	s_waitcnt lgkmcnt(1)
	v_mfma_f32_16x16x32_bf16 v[92:95], v[92:95], v[12:15], 0
	ds_read_b128 v[102:105], v122 offset:4416
	ds_read_b128 v[118:121], v122 offset:8768
	ds_read_b128 v[136:139], v122 offset:13120
	s_waitcnt lgkmcnt(3)
	v_mfma_f32_16x16x32_bf16 v[92:95], v[98:101], v[4:7], v[92:95]
	ds_read_b128 v[98:101], v122 offset:4352
	ds_read_b128 v[210:213], v122 offset:4544
	ds_read_b128 v[214:217], v122 offset:8896
	s_waitcnt lgkmcnt(2)
	v_mfma_f32_16x16x32_bf16 v[98:101], v[98:101], v[12:15], 0
	s_nop 2
	v_max3_f32 v97, v92, s52, v93
	v_mfma_f32_16x16x32_bf16 v[98:101], v[102:105], v[4:7], v[98:101]
	ds_read_b128 v[102:105], v122 offset:8704
	s_waitcnt lgkmcnt(0)
	v_mfma_f32_16x16x32_bf16 v[102:105], v[102:105], v[12:15], 0
	v_max3_f32 v97, v97, v94, v95
	s_nop 1
	v_mfma_f32_16x16x32_bf16 v[102:105], v[118:121], v[4:7], v[102:105]
	ds_read_b128 v[118:121], v122 offset:13056
	v_max3_f32 v97, v97, v98, v99
	s_waitcnt lgkmcnt(0)
	v_mfma_f32_16x16x32_bf16 v[118:121], v[118:121], v[12:15], 0
	v_max3_f32 v97, v97, v100, v101
	s_nop 0
	v_mfma_f32_16x16x32_bf16 v[160:163], v[136:139], v[4:7], v[118:121]
	s_nop 0
	v_max3_f32 v97, v97, v102, v103
	v_max3_f32 v97, v97, v104, v105
	s_nop 2
	s_nop 1
	v_max3_f32 v97, v97, v160, v161
	v_max3_f32 v97, v97, v162, v163
	v_mov_b32_e32 v106, v97
	s_nop 1
	v_permlane16_swap_b32_e32 v97, v106
	ds_read_b128 v[230:233], v122 offset:13248
	s_waitcnt lgkmcnt(1)
	v_max_f32_e32 v106, v106, v106
	v_max_f32_e32 v97, v97, v106
	v_mov_b32_e32 v106, v97
	s_nop 1
	v_permlane32_swap_b32_e32 v97, v106
	s_waitcnt lgkmcnt(0)
	v_max_f32_e32 v97, v97, v106
	v_mul_f32_e32 v97, s50, v97
	v_max_f32_e32 v131, v96, v97
	v_fma_f32 v92, v92, s50, -v131
	v_exp_f32_e32 v121, v92
	v_fma_f32 v92, v93, s50, -v131
	v_exp_f32_e32 v123, v92
	v_fma_f32 v92, v94, s50, -v131
	v_exp_f32_e32 v137, v92
	v_fma_f32 v92, v95, s50, -v131
	v_exp_f32_e32 v139, v92
	v_fma_f32 v92, v98, s50, -v131
	v_exp_f32_e32 v141, v92
	v_fma_f32 v92, v99, s50, -v131
	v_sub_f32_e32 v96, v96, v131
	v_exp_f32_e32 v143, v92
	v_fma_f32 v92, v100, s50, -v131
	v_exp_f32_e32 v145, v92
	v_fma_f32 v92, v101, s50, -v131
	v_exp_f32_e32 v116, v96
	v_exp_f32_e32 v147, v92
	v_fma_f32 v92, v102, s50, -v131
	v_exp_f32_e32 v149, v92
	v_fma_f32 v92, v103, s50, -v131
	v_pk_mul_f32 v[102:103], v[86:87], v[116:117] op_sel_hi:[1,0]
	v_pk_mul_f32 v[100:101], v[84:85], v[116:117] op_sel_hi:[1,0]
	v_pk_mul_f32 v[86:87], v[110:111], v[116:117] op_sel_hi:[1,0]
	v_pk_mul_f32 v[84:85], v[108:109], v[116:117] op_sel_hi:[1,0]
	ds_read_b128 v[108:111], v122 offset:128
	v_pk_mul_f32 v[98:99], v[82:83], v[116:117] op_sel_hi:[1,0]
	v_pk_mul_f32 v[96:97], v[80:81], v[116:117] op_sel_hi:[1,0]
	v_pk_mul_f32 v[82:83], v[114:115], v[116:117] op_sel_hi:[1,0]
	v_pk_mul_f32 v[80:81], v[112:113], v[116:117] op_sel_hi:[1,0]
	ds_read_b128 v[112:115], v122 offset:192
	s_waitcnt lgkmcnt(1)
	v_mfma_f32_16x16x32_bf16 v[108:111], v[108:111], v[8:11], 0
	v_exp_f32_e32 v151, v92
	v_fma_f32 v92, v104, s50, -v131
	s_waitcnt lgkmcnt(0)
	v_mfma_f32_16x16x32_bf16 v[108:111], v[112:115], v[16:19], v[108:111]
	ds_read_b128 v[112:115], v122 offset:4480
	v_exp_f32_e32 v153, v92
	s_waitcnt lgkmcnt(0)
	v_mfma_f32_16x16x32_bf16 v[112:115], v[112:115], v[8:11], 0
	s_nop 2
	s_nop 0
	v_max3_f32 v118, v108, s52, v109
	v_mfma_f32_16x16x32_bf16 v[112:115], v[210:213], v[16:19], v[112:115]
	ds_read_b128 v[210:213], v122 offset:8832
	s_waitcnt lgkmcnt(0)
	v_mfma_f32_16x16x32_bf16 v[210:213], v[210:213], v[8:11], 0
	v_max3_f32 v118, v118, v110, v111
	s_nop 1
	v_mfma_f32_16x16x32_bf16 v[210:213], v[214:217], v[16:19], v[210:213]
	ds_read_b128 v[214:217], v122 offset:13184
	v_max3_f32 v118, v118, v112, v113
	s_waitcnt lgkmcnt(0)
	v_mfma_f32_16x16x32_bf16 v[214:217], v[214:217], v[8:11], 0
	v_max3_f32 v118, v118, v114, v115
	s_nop 0
	v_mfma_f32_16x16x32_bf16 v[214:217], v[230:233], v[16:19], v[214:217]
	s_nop 0
	v_max3_f32 v118, v118, v210, v211
	v_max3_f32 v118, v118, v212, v213
	s_nop 2
	s_nop 1
	v_max3_f32 v118, v118, v214, v215
	v_max3_f32 v118, v118, v216, v217
	v_mov_b32_e32 v119, v118
	s_nop 1
	v_permlane16_swap_b32_e32 v118, v119
	v_fma_f32 v92, v105, s50, -v131
	v_exp_f32_e32 v155, v92
	v_fma_f32 v92, v160, s50, -v131
	s_waitcnt lgkmcnt(0)
	v_max_f32_e32 v119, v119, v119
	v_max_f32_e32 v118, v118, v119
	v_mov_b32_e32 v119, v118
	s_nop 1
	v_permlane32_swap_b32_e32 v118, v119
	v_exp_f32_e32 v157, v92
	v_fma_f32 v92, v161, s50, -v131
	s_waitcnt lgkmcnt(0)
; __device__ __forceinline__ float shx(float v, int mask, int lane) { return __int_as_float(__builtin_amdgcn_ds_bpermute((lane ^ mask) << 2, __float_as_int(v))); }
; __device__ __forceinline__ u32x2 trr(unsigned addr) { u32x2 r; asm volatile("ds_read_b64_tr_b16 %0, %1" : "=&v"(r) : "v"(addr) : "memory"); return r; }
; __device__ __forceinline__ unsigned pack2(float lo, float hi) { unsigned r; asm("v_cvt_pk_bf16_f32 %0, %1, %2" : "=v"(r) : "v"(lo), "v"(hi)); return r; }
; __device__ __forceinline__ void attn_phase(int wv, PP P, int L, LAS unsigned char* lds) {
;     ...
;                     float mx = -INFINITY;
; #pragma unroll
;                     for (int nt = 0; nt < 4; ++nt)
; #pragma unroll
;                         for (int q = 0; q < 4; ++q) { const bool kv = (kt > 0) || (nt * 16 + fq * 4 + q >= 48); sa[nt][q] = kv ? sa[nt][q] * 0.125f : -INFINITY; mx = fmaxf(mx, sa[nt][q]); }
;                     mx = fmaxf(mx, shx(mx, 16, lane)); mx = fmaxf(mx, shx(mx, 32, lane));
;                     const float mnew = fmaxf(mrun[m], mx); const float alpha = __expf(mrun[m] - mnew); mrun[m] = mnew;
;                     float rsum = 0.f;
; #pragma unroll
;                     for (int nt = 0; nt < 4; ++nt)
; #pragma unroll
;                         for (int q = 0; q < 4; ++q) { sa[nt][q] = __expf(sa[nt][q] - mnew); rsum += sa[nt][q]; }
;                     rsum += shx(rsum, 16, lane); rsum += shx(rsum, 32, lane);
;                     lrun[m] = lrun[m] * alpha + rsum;
; #pragma unroll
;                     for (int e = 0; e < 8; ++e) O[m][e] *= alpha;
; #pragma unroll
;                     for (int kp = 0; kp < 2; ++kp) { u32x4 t; t.x = pack2(sa[2 * kp][0], sa[2 * kp][1]); t.y = pack2(sa[2 * kp][2], sa[2 * kp][3]); t.z = pack2(sa[2 * kp + 1][0], sa[2 * kp + 1][1]); t.w = pack2(sa[2 * kp + 1][2], sa[2 * kp + 1][3]);
;                         pf[m][kp] = __builtin_bit_cast(bf16x8, t); }
;                 }
;                 const unsigned trv = ldsb + vbuf + (4 * fq + trq) * 272 + (4 * trp) * 2;
; #pragma unroll
;                 for (int kp = 0; kp < 2; ++kp) {
;                     u32x2 vl[8], vh[8];
; #pragma unroll
;                     for (int e = 0; e < 8; ++e) { vl[e] = trr(trv + (32 * kp) * 272 + e * 32); vh[e] = trr(trv + (32 * kp + 16) * 272 + e * 32); }
	v_max_f32_e32 v118, v118, v119
	v_mul_f32_e32 v118, s50, v118
	v_max_f32_e32 v209, v117, v118
	v_fma_f32 v108, v108, s50, -v209
	v_exp_f32_e32 v120, v108
	v_fma_f32 v108, v109, s50, -v209
	v_exp_f32_e32 v122, v108
	v_fma_f32 v108, v110, s50, -v209
	v_exp_f32_e32 v136, v108
	v_fma_f32 v108, v111, s50, -v209
	v_exp_f32_e32 v138, v108
	v_fma_f32 v108, v112, s50, -v209
	v_exp_f32_e32 v140, v108
	v_fma_f32 v108, v113, s50, -v209
	v_exp_f32_e32 v142, v108
	v_fma_f32 v108, v114, s50, -v209
	v_exp_f32_e32 v144, v108
	v_fma_f32 v108, v115, s50, -v209
	v_fma_f32 v110, v211, s50, -v209
	v_exp_f32_e32 v146, v108
	v_fma_f32 v108, v210, s50, -v209
	v_exp_f32_e32 v150, v110
	v_fma_f32 v110, v212, s50, -v209
	v_exp_f32_e32 v148, v108
	v_pk_add_f32 v[108:109], v[120:121], 0 op_sel_hi:[1,0]
	v_pk_add_f32 v[108:109], v[122:123], v[108:109]
	v_exp_f32_e32 v152, v110
	v_fma_f32 v110, v213, s50, -v209
	v_pk_add_f32 v[108:109], v[136:137], v[108:109]
	v_pk_add_f32 v[108:109], v[138:139], v[108:109]
	v_exp_f32_e32 v154, v110
	v_fma_f32 v110, v214, s50, -v209
	v_pk_add_f32 v[108:109], v[140:141], v[108:109]
	v_pk_add_f32 v[108:109], v[142:143], v[108:109]
	v_exp_f32_e32 v156, v110
	v_fma_f32 v110, v215, s50, -v209
	v_pk_add_f32 v[108:109], v[144:145], v[108:109]
	v_exp_f32_e32 v159, v92
	v_fma_f32 v92, v162, s50, -v131
	v_pk_add_f32 v[108:109], v[146:147], v[108:109]
	v_exp_f32_e32 v158, v110
	v_fma_f32 v110, v216, s50, -v209
	v_pk_add_f32 v[108:109], v[148:149], v[108:109]
	v_exp_f32_e32 v161, v92
	v_fma_f32 v92, v163, s50, -v131
	v_exp_f32_e32 v160, v110
	v_fma_f32 v110, v217, s50, -v209
	v_pk_add_f32 v[108:109], v[150:151], v[108:109]
	v_pk_add_f32 v[108:109], v[152:153], v[108:109]
	v_exp_f32_e32 v163, v92
	v_exp_f32_e32 v162, v110
	v_pk_add_f32 v[108:109], v[154:155], v[108:109]
	v_pk_mul_f32 v[106:107], v[74:75], v[116:117] op_sel_hi:[1,0]
	v_pk_add_f32 v[108:109], v[156:157], v[108:109]
	v_pk_mul_f32 v[104:105], v[72:73], v[116:117] op_sel_hi:[1,0]
	v_pk_add_f32 v[108:109], v[158:159], v[108:109]
	v_pk_mul_f32 v[94:95], v[78:79], v[116:117] op_sel_hi:[1,0]
	v_pk_add_f32 v[108:109], v[160:161], v[108:109]
	v_pk_mul_f32 v[92:93], v[76:77], v[116:117] op_sel_hi:[1,0]
	v_pk_add_f32 v[108:109], v[162:163], v[108:109]
	v_mov_b32_e32 v111, v109
	v_mov_b32_e32 v110, v108
	s_nop 0
	v_permlane16_swap_b32_e32 v109, v111
	v_permlane16_swap_b32_e32 v108, v110
	v_pk_mul_f32 v[90:91], v[90:91], v[116:117] op_sel_hi:[1,0]
	v_pk_mul_f32 v[88:89], v[88:89], v[116:117] op_sel_hi:[1,0]
	v_pk_mul_f32 v[74:75], v[70:71], v[116:117] op_sel_hi:[1,0]
	v_pk_mul_f32 v[72:73], v[68:69], v[116:117] op_sel_hi:[1,0]
	s_waitcnt lgkmcnt(0)
	v_pk_add_f32 v[108:109], v[108:109], v[110:111]
	v_sub_f32_e32 v117, v117, v209
	v_mov_b32_e32 v111, v109
	v_mov_b32_e32 v110, v108
	s_nop 0
	v_permlane32_swap_b32_e32 v109, v111
	v_permlane32_swap_b32_e32 v108, v110
	v_exp_f32_e32 v214, v117
	v_mov_b32_e32 v215, v116
	v_add_u32_e32 v216, s7, v167
	s_waitcnt lgkmcnt(0)
	v_pk_add_f32 v[108:109], v[108:109], v[110:111]
	v_pk_mul_f32 v[116:117], v[40:41], v[214:215] op_sel_hi:[1,0]
	v_pk_fma_f32 v[134:135], v[134:135], v[214:215], v[108:109]
	v_pk_mul_f32 v[108:109], v[44:45], v[214:215] op_sel_hi:[1,0]
	v_pk_mul_f32 v[44:45], v[56:57], v[214:215] op_sel_hi:[1,0]
	v_pk_mul_f32 v[40:41], v[60:61], v[214:215] op_sel_hi:[1,0]
	v_add_u32_e32 v56, 0x8800, v216
	ds_read_b64_tr_b16 v[60:61], v56
	v_pk_mul_f32 v[118:119], v[42:43], v[214:215] op_sel_hi:[1,0]
	v_pk_mul_f32 v[42:43], v[62:63], v[214:215] op_sel_hi:[1,0]
	v_add_u32_e32 v57, 0x9900, v216
	ds_read_b64_tr_b16 v[62:63], v57
	v_cvt_pk_bf16_f32 v77, v137, v139
	v_pk_mul_f32 v[210:211], v[48:49], v[214:215] op_sel_hi:[1,0]
	v_pk_mul_f32 v[48:49], v[52:53], v[214:215] op_sel_hi:[1,0]
	v_cvt_pk_bf16_f32 v53, v136, v138
	v_add_u32_e32 v56, 0x8820, v216
	ds_read_b64_tr_b16 v[136:137], v56
	v_add_u32_e32 v56, 0x9920, v216
	ds_read_b64_tr_b16 v[138:139], v56
	v_cvt_pk_bf16_f32 v78, v141, v143
	v_pk_mul_f32 v[212:213], v[50:51], v[214:215] op_sel_hi:[1,0]
	v_pk_mul_f32 v[50:51], v[54:55], v[214:215] op_sel_hi:[1,0]
	v_cvt_pk_bf16_f32 v54, v140, v142
	v_add_u32_e32 v56, 0x8840, v216
	ds_read_b64_tr_b16 v[140:141], v56
	v_add_u32_e32 v56, 0x9940, v216
	ds_read_b64_tr_b16 v[142:143], v56
	v_cvt_pk_bf16_f32 v79, v145, v147
	v_cvt_pk_bf16_f32 v55, v144, v146
	v_add_u32_e32 v56, 0x8860, v216
	ds_read_b64_tr_b16 v[144:145], v56
	v_add_u32_e32 v56, 0x9960, v216
	ds_read_b64_tr_b16 v[146:147], v56
	v_cvt_pk_bf16_f32 v68, v149, v151
	v_pk_mul_f32 v[112:113], v[36:37], v[214:215] op_sel_hi:[1,0]
	v_pk_mul_f32 v[36:37], v[64:65], v[214:215] op_sel_hi:[1,0]
	v_cvt_pk_bf16_f32 v64, v148, v150
	v_add_u32_e32 v56, 0x8880, v216
	ds_read_b64_tr_b16 v[148:149], v56
	v_add_u32_e32 v56, 0x9980, v216
	ds_read_b64_tr_b16 v[150:151], v56
	v_cvt_pk_bf16_f32 v69, v153, v155
	v_cvt_pk_bf16_f32 v65, v152, v154
	v_add_u32_e32 v56, 0x88a0, v216
	ds_read_b64_tr_b16 v[152:153], v56
	v_add_u32_e32 v56, 0x99a0, v216
	ds_read_b64_tr_b16 v[154:155], v56
	v_cvt_pk_bf16_f32 v70, v157, v159
	v_pk_mul_f32 v[114:115], v[38:39], v[214:215] op_sel_hi:[1,0]
	v_pk_mul_f32 v[38:39], v[66:67], v[214:215] op_sel_hi:[1,0]
	v_cvt_pk_bf16_f32 v66, v156, v158
	v_add_u32_e32 v56, 0x88c0, v216
	ds_read_b64_tr_b16 v[156:157], v56
	v_add_u32_e32 v56, 0x99c0, v216
	ds_read_b64_tr_b16 v[158:159], v56
	v_cvt_pk_bf16_f32 v76, v121, v123
	v_cvt_pk_bf16_f32 v52, v120, v122
	v_add_u32_e32 v56, 0x88e0, v216
	ds_read_b64_tr_b16 v[120:121], v56
	v_add_u32_e32 v56, 0x99e0, v216
	ds_read_b64_tr_b16 v[122:123], v56
	s_waitcnt lgkmcnt(0)
; __device__ __forceinline__ u32x2 trr(unsigned addr) { u32x2 r; asm volatile("ds_read_b64_tr_b16 %0, %1" : "=&v"(r) : "v"(addr) : "memory"); return r; }
; __device__ __forceinline__ void trw4(u32x2& a, u32x2& b, u32x2& c, u32x2& d) { asm volatile("s_waitcnt lgkmcnt(0)" : "+v"(a), "+v"(b), "+v"(c), "+v"(d) : : "memory"); }
; __device__ __forceinline__ void attn_phase(int wv, PP P, int L, LAS unsigned char* lds) {
;     ...
;                 const unsigned trv = ldsb + vbuf + (4 * fq + trq) * 272 + (4 * trp) * 2;
; #pragma unroll
;                 for (int kp = 0; kp < 2; ++kp) {
;                     u32x2 vl[8], vh[8];
; #pragma unroll
;                     for (int e = 0; e < 8; ++e) { vl[e] = trr(trv + (32 * kp) * 272 + e * 32); vh[e] = trr(trv + (32 * kp + 16) * 272 + e * 32); }
;                     trw4(vl[0], vl[1], vl[2], vl[3]); trw4(vl[4], vl[5], vl[6], vl[7]); trw4(vh[0], vh[1], vh[2], vh[3]); trw4(vh[4], vh[5], vh[6], vh[7]);
; #pragma unroll
;                     for (int e = 0; e < 8; ++e) { const bf16x8 vf = mk8(vl[e], vh[e]);
;                         O[0][e] = __builtin_amdgcn_mfma_f32_16x16x32_bf16(vf, pf[0][kp], O[0][e], 0, 0, 0);
;                         O[1][e] = __builtin_amdgcn_mfma_f32_16x16x32_bf16(vf, pf[1][kp], O[1][e], 0, 0, 0); }
;                 }
	s_waitcnt lgkmcnt(0)
	s_waitcnt lgkmcnt(0)
	v_pk_mul_f32 v[110:111], v[46:47], v[214:215] op_sel_hi:[1,0]
	v_pk_mul_f32 v[46:47], v[58:59], v[214:215] op_sel_hi:[1,0]
	s_waitcnt lgkmcnt(0)
	v_mfma_f32_16x16x32_bf16 v[56:59], v[60:63], v[76:79], v[104:107]
	v_cvt_pk_bf16_f32 v71, v161, v163
	v_cvt_pk_bf16_f32 v67, v160, v162
	v_mfma_f32_16x16x32_bf16 v[100:103], v[136:139], v[76:79], v[100:103]
	v_mfma_f32_16x16x32_bf16 v[104:107], v[136:139], v[52:55], v[116:119]
	v_mfma_f32_16x16x32_bf16 v[96:99], v[140:143], v[76:79], v[96:99]
	v_mfma_f32_16x16x32_bf16 v[112:115], v[140:143], v[52:55], v[112:115]
	v_mfma_f32_16x16x32_bf16 v[136:139], v[152:155], v[76:79], v[84:87]
	v_mfma_f32_16x16x32_bf16 v[140:143], v[152:155], v[52:55], v[44:47]
	v_mfma_f32_16x16x32_bf16 v[152:155], v[120:123], v[76:79], v[72:75]
	s_nop 1
	v_add_u32_e32 v44, 0xbb20, v216
	v_add_u32_e32 v46, 0xaa40, v216
	v_mfma_f32_16x16x32_bf16 v[120:123], v[120:123], v[52:55], v[36:39]
	s_nop 2
	v_add_u32_e32 v38, 0xaa00, v216
	ds_read_b64_tr_b16 v[36:37], v38
	v_mfma_f32_16x16x32_bf16 v[88:91], v[148:151], v[76:79], v[88:91]
	v_mfma_f32_16x16x32_bf16 v[116:119], v[148:151], v[52:55], v[48:51]
	v_mfma_f32_16x16x32_bf16 v[148:151], v[156:159], v[52:55], v[40:43]
	s_nop 1
	v_add_u32_e32 v48, 0xbb40, v216
	v_add_u32_e32 v40, 0xbb00, v216
	ds_read_b64_tr_b16 v[38:39], v40
	v_add_u32_e32 v42, 0xaa20, v216
	ds_read_b64_tr_b16 v[40:41], v42
	ds_read_b64_tr_b16 v[42:43], v44
	ds_read_b64_tr_b16 v[44:45], v46
	ds_read_b64_tr_b16 v[46:47], v48
	v_mfma_f32_16x16x32_bf16 v[60:63], v[60:63], v[52:55], v[210:213]
	v_add_u32_e32 v48, 0xaa60, v216
	v_mfma_f32_16x16x32_bf16 v[108:111], v[144:147], v[52:55], v[108:111]
	ds_read_b64_tr_b16 v[52:53], v48
	v_add_u32_e32 v48, 0xbb60, v216
	ds_read_b64_tr_b16 v[54:55], v48
	v_mfma_f32_16x16x32_bf16 v[92:95], v[144:147], v[76:79], v[92:95]
	v_add_u32_e32 v48, 0xaa80, v216
	v_mfma_f32_16x16x32_bf16 v[144:147], v[156:159], v[76:79], v[80:83]
	ds_read_b64_tr_b16 v[156:157], v48
	v_add_u32_e32 v48, 0xbb80, v216
	ds_read_b64_tr_b16 v[158:159], v48
	v_add_u32_e32 v48, 0xaaa0, v216
	ds_read_b64_tr_b16 v[160:161], v48
	v_add_u32_e32 v48, 0xbba0, v216
	ds_read_b64_tr_b16 v[162:163], v48
	v_add_u32_e32 v48, 0xaac0, v216
	ds_read_b64_tr_b16 v[210:211], v48
	v_add_u32_e32 v48, 0xbbc0, v216
	ds_read_b64_tr_b16 v[212:213], v48
	v_add_u32_e32 v48, 0xaae0, v216
	ds_read_b64_tr_b16 v[214:215], v48
	v_add_u32_e32 v48, 0xbbe0, v216
	ds_read_b64_tr_b16 v[216:217], v48
	s_waitcnt lgkmcnt(0)
	s_waitcnt lgkmcnt(0)
	s_waitcnt lgkmcnt(0)
	s_nop 0
	s_waitcnt lgkmcnt(0)
	v_mfma_f32_16x16x32_bf16 v[72:75], v[36:39], v[68:71], v[56:59]
	v_mfma_f32_16x16x32_bf16 v[48:51], v[36:39], v[64:67], v[60:63]
	v_mfma_f32_16x16x32_bf16 v[84:87], v[40:43], v[68:71], v[100:103]
	v_mfma_f32_16x16x32_bf16 v[40:43], v[40:43], v[64:67], v[104:107]
	v_mfma_f32_16x16x32_bf16 v[80:83], v[44:47], v[68:71], v[96:99]
	v_mfma_f32_16x16x32_bf16 v[36:39], v[44:47], v[64:67], v[112:115]
	s_nop 1
	v_mov_b32_e32 v96, v131
	v_mfma_f32_16x16x32_bf16 v[76:79], v[52:55], v[68:71], v[92:95]
	v_mfma_f32_16x16x32_bf16 v[44:47], v[52:55], v[64:67], v[108:111]
	v_mfma_f32_16x16x32_bf16 v[88:91], v[156:159], v[68:71], v[88:91]
	v_mfma_f32_16x16x32_bf16 v[52:55], v[156:159], v[64:67], v[116:119]
	v_mfma_f32_16x16x32_bf16 v[108:111], v[160:163], v[68:71], v[136:139]
	s_nop 1
	v_mov_b32_e32 v117, v209
	v_mfma_f32_16x16x32_bf16 v[56:59], v[160:163], v[64:67], v[140:143]
	v_mfma_f32_16x16x32_bf16 v[112:115], v[210:213], v[68:71], v[144:147]
	v_mfma_f32_16x16x32_bf16 v[60:63], v[210:213], v[64:67], v[148:151]
	v_mfma_f32_16x16x32_bf16 v[68:71], v[214:217], v[68:71], v[152:155]
	v_mfma_f32_16x16x32_bf16 v[64:67], v[214:217], v[64:67], v[120:123]
	s_cmp_eq_u32 s24, s6
	s_cbranch_scc1 .LBB0_375
